# speedup vs baseline: 1.1383x; 1.0070x over previous
; DEV int tidx() { int t = threadIdx.x; asm volatile("" : "+v"(t)); return t; }
; DEV int bidx() { int b = __builtin_amdgcn_readfirstlane(blockIdx.x); asm volatile("" : "+s"(b)); return b; }
; DEV int gdim() { int g = __builtin_amdgcn_readfirstlane(gridDim.x); asm volatile("" : "+s"(g)); return g; }
; #define ws (wsp(p))
; DEV void phase_m2(const Params& p, int layer) {
;   const int lane = tidx() & 63, w = tidx() >> 6;
;   char* ws = wsp(p);
;   const float* small = (const float*)(ws + OFF_B);
;   u16* cqn = (u16*)(ws + E_CQN);
;   u16* ckp = (u16*)(ws + E_CKP);
;   u16* krp = (u16*)(ws + E_KRP);
;   u16* ckc = (u16*)(ws + D_CKC);
;   u16* krc = (u16*)(ws + D_KRC);
;   u16* vtc = (u16*)(ws + A_VTC);
;   float* AB = (float*)(ws + E_AB);
;   const float* qg = p.in[12] + layer * 384;
;   const float* kvg = p.in[14] + layer * 256;
;   for (int t = bidx() * 4 + w; t < T_ALL; t += gdim() * 4) {
;     const float* s = small + (size_t)t * 768;
;     const bool pr = t < T_P;
;     const int b = pr ? (t >> 13) : ((t - T_P) >> 5);
;     const int i = pr ? (t & 8191) : ((t - T_P) & 31);
;     const int pos = pr ? i : 4096 + i;
.LBB0_204:
	s_or_b64 exec, exec, s[0:1]
	v_mov_b32_e32 v0, v157
	v_mov_b32_e32 v2, v157
	s_barrier
	s_mov_b64 s[0:1], s[62:63]
	v_ashrrev_i32_e32 v2, 6, v2
	s_mov_b32 s2, s52
	s_nop 0
	v_lshl_add_u32 v2, s2, 2, v2
	v_cmp_gt_i32_e32 vcc, s72, v2
	s_and_saveexec_b64 s[12:13], vcc
	s_cbranch_execz .LBB0_237
	s_add_u32 s14, s0, 0x1c868000
	s_addc_u32 s15, s1, 0
	s_add_u32 s16, s0, 0x16d00000
	s_addc_u32 s17, s1, 0
	s_add_u32 s18, s0, 0xc980000
	v_readlane_b32 s10, v254, 58
	s_addc_u32 s19, s1, 0
	s_mov_b32 s5, s93
	s_lshl_b32 s4, s10, 8
	v_readlane_b32 s36, v254, 0
	s_lshl_b64 s[2:3], s[4:5], 2
	v_readlane_b32 s48, v254, 12
	v_readlane_b32 s49, v254, 13
	s_add_u32 s6, s48, s2
	s_mul_i32 s4, s10, 0x180
	v_readlane_b32 s44, v254, 8
	s_addc_u32 s7, s49, s3
	s_lshl_b64 s[2:3], s[4:5], 2
	v_readlane_b32 s45, v254, 9
	s_add_u32 s8, s44, s2
	s_addc_u32 s9, s45, s3
	v_and_b32_e32 v3, 31, v0
	v_lshlrev_b32_e32 v3, 3, v3
	s_getpc_b64 s[2:3]
	s_add_u32 s2, s2, _ZL8ROPE_REV@rel32@lo+4
	s_addc_u32 s3, s3, _ZL8ROPE_REV@rel32@hi+12
	global_load_dwordx2 v[4:5], v3, s[2:3]
	v_and_b32_e32 v6, 63, v0
	v_and_b32_e32 v0, 64, v203
	v_add_u32_e32 v0, 64, v0
	v_xor_b32_e32 v3, 32, v203
	v_cmp_lt_i32_e32 vcc, v3, v0
	v_readlane_b32 s50, v254, 14
	v_readlane_b32 s51, v254, 15
	v_cndmask_b32_e32 v3, v203, v3, vcc
	v_lshlrev_b32_e32 v7, 2, v3
	v_xor_b32_e32 v3, 16, v203
	v_cmp_lt_i32_e32 vcc, v3, v0
	v_lshl_add_u32 v24, s10, 3, v6
	v_mov_b32_e32 v25, v1
	v_cndmask_b32_e32 v3, v203, v3, vcc
	v_lshlrev_b32_e32 v15, 2, v3
	v_xor_b32_e32 v3, 8, v203
	v_cmp_lt_i32_e32 vcc, v3, v0
	v_readlane_b32 s37, v254, 1
	v_readlane_b32 s38, v254, 2
	v_cndmask_b32_e32 v3, v203, v3, vcc
	v_lshlrev_b32_e32 v17, 2, v3
	v_xor_b32_e32 v3, 4, v203
	v_cmp_lt_i32_e32 vcc, v3, v0
	v_readlane_b32 s39, v254, 3
	v_readlane_b32 s42, v254, 6
	v_cndmask_b32_e32 v3, v203, v3, vcc
	v_lshlrev_b32_e32 v19, 2, v3
	v_xor_b32_e32 v3, 2, v203
	v_cmp_lt_i32_e32 vcc, v3, v0
	v_readlane_b32 s43, v254, 7
	v_readlane_b32 s50, v254, 61
	v_cndmask_b32_e32 v3, v203, v3, vcc
	v_lshlrev_b32_e32 v58, 2, v3
	v_xor_b32_e32 v3, 1, v203
	v_cmp_lt_i32_e32 vcc, v3, v0
	s_mov_b64 s[2:3], 0x1b008000
	v_lshlrev_b64 v[26:27], 2, v[24:25]
	v_cndmask_b32_e32 v0, v203, v3, vcc
	v_lshlrev_b32_e32 v59, 2, v0
	v_lshlrev_b32_e32 v0, 1, v6
	v_lshl_add_u64 v[8:9], s[0:1], 0, v[0:1]
	v_lshlrev_b32_e32 v0, 2, v6
	v_lshl_add_u64 v[28:29], s[0:1], 0, v[0:1]
	s_mov_b64 s[0:1], 0x1ae00000
	v_lshl_add_u64 v[12:13], v[28:29], 0, s[0:1]
	s_mov_b64 s[0:1], 0xeb00000
	s_mov_b64 s[42:43], 0x1ffff
	v_readlane_b32 s51, v254, 62
	s_mov_b64 s[44:45], 0x3fff
	v_lshl_add_u64 v[10:11], v[8:9], 0, s[2:3]
	s_lshl_b32 s22, s10, 4
	s_lshl_b32 s23, s10, 2
	v_cmp_gt_u32_e32 vcc, 32, v6
	v_cmp_lt_u32_e64 s[2:3], 7, v6
	v_cmp_gt_u32_e64 s[4:5], 16, v6
	v_or_b32_e32 v14, 64, v6
	v_or_b32_e32 v16, 0x80, v6
	v_or_b32_e32 v18, 0xc0, v6
	v_lshl_add_u64 v[20:21], s[8:9], 0, v[0:1]
	v_lshl_add_u64 v[22:23], s[6:7], 0, v[0:1]
	v_lshl_add_u64 v[24:25], s[38:39], 0, v[26:27]
	s_mov_b32 s39, 0x8000
	v_lshl_add_u64 v[26:27], s[36:37], 0, v[26:27]
	v_lshl_add_u64 v[28:29], v[28:29], 0, s[0:1]
	s_mov_b64 s[20:21], 0
	v_readlane_b32 s40, v254, 4
	v_readlane_b32 s41, v254, 5
	v_readlane_b32 s46, v254, 10
	v_readlane_b32 s47, v254, 11
	global_load_dword v222, v[22:23], off
	global_load_dword v223, v[22:23], off offset:256
	global_load_dword v224, v[22:23], off offset:512
	global_load_dword v225, v[22:23], off offset:768
	s_mov_b64 s[100:101], exec
	s_mov_b64 exec, 0xff
	global_load_dword v228, v[24:25], off
	global_load_dword v229, v[26:27], off
	s_mov_b64 exec, s[100:101]
	s_branch .LBB0_207

; DEV int bidx() { int b = __builtin_amdgcn_readfirstlane(blockIdx.x); asm volatile("" : "+s"(b)); return b; }
; DEV int gdim() { int g = __builtin_amdgcn_readfirstlane(gridDim.x); asm volatile("" : "+s"(g)); return g; }
; DEV void phase_m2(const Params& p, int layer) {
;     ...
;   for (int t = bidx() * 4 + w; t < T_ALL; t += gdim() * 4) {
;     const float* s = small + (size_t)t * 768;
;     const bool pr = t < T_P;
;     const int b = pr ? (t >> 13) : ((t - T_P) >> 5);
;     const int i = pr ? (t & 8191) : ((t - T_P) & 31);
;     const int pos = pr ? i : 4096 + i;
;     {
;       float x[6], ss = 0.f;
; #pragma unroll
;       for (int k = 0; k < 6; k++) { x[k] = s[lane + 64 * k]; ss += x[k] * x[k]; }
;       ss = wave_sum(ss);
;       const float r = rsqrtf(ss * (1.f / 384.f) + EPS_);
; #pragma unroll
;       for (int k = 0; k < 6; k++) cqn[(size_t)t * 384 + lane + 64 * k] = f2bf(x[k] * r * qg[lane + 64 * k]);
;     }
;     {
;       float x[4], ss = 0.f;
; #pragma unroll
;       for (int k = 0; k < 4; k++) { x[k] = s[384 + lane + 64 * k]; ss += x[k] * x[k]; }
;       ss = wave_sum(ss);
;       const float r = rsqrtf(ss * (1.f / 256.f) + EPS_);
; #pragma unroll
;       for (int k = 0; k < 4; k++) {
;         const int c = lane + 64 * k;
;         const float v = x[k] * r * kvg[c];
;         const u16 hv = f2bf(v);
;         if (pr) {
;           p.out[O_PCKV + ((size_t)(layer * 4 + b) * 8192 + i) * 256 + c] = v;
;           ckp[(size_t)t * 256 + c] = hv;
.LBB0_207:
	v_mad_i64_i32 v[30:31], s[0:1], v2, s68, v[28:29]
	global_load_dword v226, v[30:31], off offset:2560
	global_load_dword v227, v[30:31], off offset:2816
	global_load_dword v32, v[30:31], off
	global_load_dword v33, v[30:31], off offset:256
	global_load_dword v36, v[30:31], off offset:512
	global_load_dword v37, v[30:31], off offset:768
	v_add_u32_e32 v0, 0xffff8000, v2
	v_lshrrev_b32_e32 v3, 5, v0
	global_load_dword v42, v[30:31], off offset:1024
	global_load_dword v43, v[30:31], off offset:1280
	v_mad_i64_i32 v[48:49], s[0:1], v2, s55, v[10:11]
	s_mov_b32 s0, 0x3b800000
	s_mov_b32 s1, 0x3b2aaaab
	v_and_b32_e32 v60, 31, v2
	v_cmp_lt_i32_e64 s[6:7], s74, v2
	s_waitcnt vmcnt(4)
	v_mul_f32_e32 v0, v33, v33
	v_pk_fma_f32 v[34:35], v[32:33], v[32:33], v[0:1] op_sel_hi:[1,1,0]
	global_load_dword v0, v[20:21], off
	global_load_dword v56, v[20:21], off offset:256
	global_load_dword v57, v[20:21], off offset:512
	global_load_dword v61, v[20:21], off offset:768
	global_load_dword v62, v[20:21], off offset:1024
	global_load_dword v63, v[20:21], off offset:1280
	global_load_dword v44, v[30:31], off offset:1536
	global_load_dword v45, v[30:31], off offset:1792
	s_waitcnt vmcnt(10)
	v_pk_fma_f32 v[40:41], v[36:37], v[36:37], v[34:35]
	global_load_dword v34, v[30:31], off offset:2048
	global_load_dword v35, v[30:31], off offset:2304
	v_pk_mul_f32 v[38:39], v[36:37], v[36:37]
	s_waitcnt vmcnt(10)
	v_pk_mul_f32 v[46:47], v[42:43], v[42:43]
	v_mov_b32_e32 v55, v40
	v_mov_b32_e32 v41, v46
	s_waitcnt vmcnt(2)
	v_pk_mul_f32 v[50:51], v[44:45], v[44:45]
	s_nop 0
	v_mov_b32_e32 v54, v50
	s_waitcnt vmcnt(0)
	v_pk_mul_f32 v[52:53], v[34:35], v[34:35]
	v_mov_b32_e32 v38, v51
	v_pk_add_f32 v[38:39], v[54:55], v[38:39]
	v_mov_b32_e32 v40, v52
	v_pk_add_f32 v[38:39], v[38:39], v[40:41]
	v_mov_b32_e32 v46, v53
	v_pk_add_f32 v[38:39], v[38:39], v[46:47]
	ds_bpermute_b32 v41, v7, v39
	ds_bpermute_b32 v40, v7, v38
	v_lshlrev_b32_e32 v46, 2, v6
	v_lshlrev_b32_e32 v52, 1, v6
	s_waitcnt lgkmcnt(0)
	v_pk_add_f32 v[38:39], v[38:39], v[40:41]
	ds_bpermute_b32 v41, v15, v39
	ds_bpermute_b32 v40, v15, v38
	s_waitcnt lgkmcnt(0)
	v_pk_add_f32 v[38:39], v[38:39], v[40:41]
	ds_bpermute_b32 v41, v17, v39
	ds_bpermute_b32 v40, v17, v38
	s_waitcnt lgkmcnt(0)
	v_pk_add_f32 v[38:39], v[38:39], v[40:41]
	ds_bpermute_b32 v41, v19, v39
	ds_bpermute_b32 v40, v19, v38
	s_waitcnt lgkmcnt(0)
	v_pk_add_f32 v[38:39], v[38:39], v[40:41]
	ds_bpermute_b32 v41, v58, v39
	ds_bpermute_b32 v40, v58, v38
	s_waitcnt lgkmcnt(0)
	v_pk_add_f32 v[38:39], v[38:39], v[40:41]
	ds_bpermute_b32 v41, v59, v39
	ds_bpermute_b32 v40, v59, v38
	s_waitcnt lgkmcnt(0)
	v_pk_add_f32 v[38:39], v[38:39], v[40:41]
	s_nop 0
	v_pk_fma_f32 v[38:39], v[38:39], s[0:1], v[156:157] op_sel_hi:[1,1,0]
	v_mov_b32_e32 v41, v1
	v_mul_f32_e32 v40, 0x4b800000, v39
	v_cmp_gt_f32_e64 s[10:11], s75, v39
	v_cmp_gt_f32_e64 s[8:9], s75, v38
	s_nop 0
	v_cndmask_b32_e64 v39, v39, v40, s[10:11]
	v_rsq_f32_e32 v39, v39
	s_nop 0
	v_mul_f32_e32 v40, 0x45800000, v39
	v_cndmask_b32_e64 v39, v39, v40, s[10:11]
	v_mul_f32_e32 v32, v32, v39
	v_mul_f32_e32 v0, v0, v32
	v_cvt_pk_bf16_f32 v0, v0, s0
	global_store_short v[48:49], v0, off
	v_mul_f32_e32 v0, v33, v39
	v_mul_f32_e32 v0, v56, v0
	v_cvt_pk_bf16_f32 v0, v0, s0
	global_store_short v[48:49], v0, off offset:128
	v_mul_f32_e32 v0, v36, v39
	v_mul_f32_e32 v0, v57, v0
	v_cvt_pk_bf16_f32 v0, v0, s0
	global_store_short v[48:49], v0, off offset:256
	v_mul_f32_e32 v0, v37, v39
	v_mul_f32_e32 v0, v61, v0
	v_cvt_pk_bf16_f32 v0, v0, s0
	global_store_short v[48:49], v0, off offset:384
	v_mul_f32_e32 v0, v42, v39
	v_mul_f32_e32 v0, v62, v0
	v_cvt_pk_bf16_f32 v0, v0, s0
	global_store_short v[48:49], v0, off offset:512
	v_mul_f32_e32 v0, v43, v39
	v_mul_f32_e32 v0, v0, v63
	v_cvt_pk_bf16_f32 v0, v0, s0
	global_store_short v[48:49], v0, off offset:640
	v_mul_f32_e32 v0, 0x4b800000, v38
	v_cndmask_b32_e64 v0, v38, v0, s[8:9]
	v_rsq_f32_e32 v0, v0
	v_lshlrev_b32_e32 v36, 10, v60
	v_mov_b32_e32 v37, v1
	s_mov_b64 s[0:1], 0xe768000
	v_mul_f32_e32 v32, 0x45800000, v0
	v_cndmask_b32_e64 v61, v0, v32, s[8:9]
	v_add_u32_e32 v0, s22, v3
	v_lshlrev_b64 v[32:33], 15, v[0:1]
	v_lshl_add_u64 v[32:33], s[60:61], 0, v[32:33]
	v_lshl_add_u64 v[32:33], v[32:33], 0, v[36:37]
	v_lshl_add_u64 v[38:39], v[32:33], 0, s[0:1]
	s_movk_i32 s0, 0x1020
	v_mad_u64_u32 v[32:33], s[0:1], v3, s0, 0
	v_or_b32_e32 v32, v32, v60
	s_mov_b64 s[0:1], 0x1000
	v_lshl_add_u64 v[32:33], v[32:33], 0, s[0:1]
	v_lshlrev_b64 v[36:37], 9, v[32:33]
	v_lshl_add_u64 v[42:43], s[16:17], 0, v[36:37]
	v_mad_u64_u32 v[36:37], s[0:1], v3, s72, v[158:159]
	v_mul_f32_e32 v3, v44, v61
	v_mov_b32_e32 v44, v222
	v_lshlrev_b32_e32 v40, 1, v60
	v_lshl_add_u64 v[40:41], s[18:19], 0, v[40:41]
	v_mul_f32_e32 v53, v44, v3
	v_cvt_pk_bf16_f32 v44, v53, s0
	s_and_saveexec_b64 s[0:1], s[6:7]
	s_xor_b64 s[0:1], exec, s[0:1]
	s_cbranch_execz .LBB0_209
	v_mov_b32_e32 v47, v1
	v_lshl_add_u64 v[48:49], v[38:39], 0, v[46:47]
	global_store_dword v[48:49], v53, off
	v_mov_b32_e32 v53, v1
	v_lshl_add_u64 v[48:49], v[42:43], 0, v[52:53]
	global_store_short v[48:49], v44, off
	v_or_b32_e32 v48, v36, v6
	v_mov_b32_e32 v49, v37
	v_lshlrev_b64 v[48:49], 6, v[48:49]
	v_lshl_add_u64 v[48:49], v[40:41], 0, v[48:49]
	global_store_short v[48:49], v44, off

; DEV void phase_m2(const Params& p, int layer) {
;     ...
;       for (int k = 0; k < 4; k++) {
;         const int c = lane + 64 * k;
;         const float v = x[k] * r * kvg[c];
;         const u16 hv = f2bf(v);
;         if (pr) {
;           p.out[O_PCKV + ((size_t)(layer * 4 + b) * 8192 + i) * 256 + c] = v;
;           ckp[(size_t)t * 256 + c] = hv;
;         } else {
;           p.out[O_SCKV + ((size_t)(layer * 16 + b) * 32 + i) * 256 + c] = v;
;           ckc[((size_t)b * 4128 + 4096 + i) * 256 + c] = hv;
;           vtc[(((size_t)b * 130 + 128) * 256 + c) * 32 + i] = hv;
;         }
;       }
.LBB0_211:
	s_or_b64 exec, exec, s[0:1]
	v_mov_b32_e32 v44, v223
	v_mul_f32_e32 v45, v45, v61
	v_mul_f32_e32 v49, v45, v44
	v_cvt_pk_bf16_f32 v47, v49, s0
	v_lshlrev_b32_e32 v44, 2, v14
	s_and_saveexec_b64 s[0:1], s[6:7]
	s_xor_b64 s[0:1], exec, s[0:1]
	s_cbranch_execz .LBB0_213
	v_mov_b32_e32 v45, v1
	v_lshl_add_u64 v[44:45], v[38:39], 0, v[44:45]
	v_mov_b32_e32 v53, v1
	global_store_dword v[44:45], v49, off
	v_lshl_add_u64 v[44:45], v[42:43], 0, v[52:53]
	global_store_short v[44:45], v47, off offset:128
	v_or_b32_e32 v44, v36, v14
	v_mov_b32_e32 v45, v37
	v_lshlrev_b64 v[44:45], 6, v[44:45]
	v_lshl_add_u64 v[44:45], v[40:41], 0, v[44:45]
	global_store_short v[44:45], v47, off

; DEV void phase_m2(const Params& p, int layer) {
;     ...
;       for (int k = 0; k < 4; k++) {
;         const int c = lane + 64 * k;
;         const float v = x[k] * r * kvg[c];
;         const u16 hv = f2bf(v);
;         if (pr) {
;           p.out[O_PCKV + ((size_t)(layer * 4 + b) * 8192 + i) * 256 + c] = v;
;           ckp[(size_t)t * 256 + c] = hv;
;         } else {
;           p.out[O_SCKV + ((size_t)(layer * 16 + b) * 32 + i) * 256 + c] = v;
;           ckc[((size_t)b * 4128 + 4096 + i) * 256 + c] = hv;
;           vtc[(((size_t)b * 130 + 128) * 256 + c) * 32 + i] = hv;
;         }
;       }
.LBB0_215:
	s_or_b64 exec, exec, s[0:1]
	v_mov_b32_e32 v44, v224
	v_mul_f32_e32 v34, v34, v61
	v_mul_f32_e32 v47, v34, v44
	v_cvt_pk_bf16_f32 v34, v47, s0
	v_lshlrev_b32_e32 v44, 2, v16
	s_and_saveexec_b64 s[0:1], s[6:7]
	s_xor_b64 s[0:1], exec, s[0:1]
	s_cbranch_execz .LBB0_217
	v_mov_b32_e32 v45, v1
	v_lshl_add_u64 v[44:45], v[38:39], 0, v[44:45]
	v_mov_b32_e32 v53, v1
	global_store_dword v[44:45], v47, off
	v_lshl_add_u64 v[44:45], v[42:43], 0, v[52:53]
	global_store_short v[44:45], v34, off offset:256
	v_or_b32_e32 v44, v36, v16
	v_mov_b32_e32 v45, v37
	v_lshlrev_b64 v[44:45], 6, v[44:45]
	v_lshl_add_u64 v[44:45], v[40:41], 0, v[44:45]
	global_store_short v[44:45], v34, off

; DEV void phase_m2(const Params& p, int layer) {
;     ...
;       for (int k = 0; k < 4; k++) {
;         const int c = lane + 64 * k;
;         const float v = x[k] * r * kvg[c];
;         const u16 hv = f2bf(v);
;         if (pr) {
;           p.out[O_PCKV + ((size_t)(layer * 4 + b) * 8192 + i) * 256 + c] = v;
;           ckp[(size_t)t * 256 + c] = hv;
;         } else {
;           p.out[O_SCKV + ((size_t)(layer * 16 + b) * 32 + i) * 256 + c] = v;
;           ckc[((size_t)b * 4128 + 4096 + i) * 256 + c] = hv;
;           vtc[(((size_t)b * 130 + 128) * 256 + c) * 32 + i] = hv;
;         }
;       }
.LBB0_219:
	s_or_b64 exec, exec, s[0:1]
	v_mov_b32_e32 v34, v225
	v_mul_f32_e32 v35, v35, v61
	v_mul_f32_e32 v47, v35, v34
	v_cvt_pk_bf16_f32 v45, v47, s0
	v_lshlrev_b32_e32 v34, 2, v18
	s_and_saveexec_b64 s[0:1], s[6:7]
	s_xor_b64 s[0:1], exec, s[0:1]
	s_cbranch_execz .LBB0_221
	v_mov_b32_e32 v35, v1
	v_lshl_add_u64 v[34:35], v[38:39], 0, v[34:35]
	v_mov_b32_e32 v53, v1
	global_store_dword v[34:35], v47, off
	v_lshl_add_u64 v[34:35], v[42:43], 0, v[52:53]
	v_or_b32_e32 v36, v36, v18
	global_store_short v[34:35], v45, off offset:384
	v_lshlrev_b64 v[34:35], 6, v[36:37]
	v_or_b32_e32 v44, 0x1000, v60
	v_lshl_add_u64 v[34:35], v[40:41], 0, v[34:35]
	global_store_short v[34:35], v45, off

; DEV void phase_m2(const Params& p, int layer) {
;     ...
;     {
;       const float x = s[640 + lane];
;       const float o = __shfl_xor(x, 32);
;       float c, sn;
;       rope_cs(pos, lane & 31, c, sn);
;       const float y = (lane < 32) ? (x * c - o * sn) : (o * sn + x * c);
;       const u16 hv = f2bf(y);
;       if (pr) {
;         p.out[O_PKR + ((size_t)(layer * 4 + b) * 8192 + i) * 64 + lane] = y;
;         krp[(size_t)t * 64 + lane] = hv;
;       } else {
;         p.out[O_SKR + ((size_t)(layer * 16 + b) * 32 + i) * 64 + lane] = y;
;         krc[((size_t)b * 4128 + 4096 + i) * 64 + lane] = hv;
;       }
.LBB0_223:
	s_or_b64 exec, exec, s[0:1]
	v_mov_b32_e32 v38, v226
	ds_bpermute_b32 v39, v7, v38
	s_and_saveexec_b64 s[0:1], s[6:7]
	s_xor_b64 s[0:1], exec, s[0:1]
	v_lshlrev_b64 v[34:35], 13, v[0:1]
	v_lshl_add_u64 v[34:35], s[60:61], 0, v[34:35]
	v_lshlrev_b32_e32 v0, 8, v60
	v_lshl_add_u64 v[34:35], v[34:35], 0, v[0:1]
	s_mov_b64 s[6:7], 0xe868000
	v_lshl_add_u64 v[34:35], v[34:35], 0, s[6:7]
	s_or_saveexec_b64 s[0:1], s[0:1]
	v_mov_b64_e32 v[36:37], 0x18d48000
	s_xor_b64 exec, exec, s[0:1]
	v_mul_hi_i32_i24_e32 v33, 0xffa00000, v48
	v_mul_i32_i24_e32 v32, 0xffa00000, v48
	v_lshl_add_u64 v[32:33], v[50:51], 0, v[32:33]
	v_lshlrev_b32_e32 v0, 8, v62
	v_lshl_add_u64 v[32:33], v[32:33], 0, v[0:1]
	s_mov_b64 s[6:7], 0xc648000
	v_lshl_add_u64 v[34:35], v[32:33], 0, s[6:7]
	v_mov_b64_e32 v[36:37], 0x1d868000
	v_mov_b64_e32 v[32:33], v[2:3]
	s_or_b64 exec, exec, s[0:1]
	v_cvt_f64_u32_e32 v[40:41], v44
	v_mul_f64 v[42:43], v[4:5], v[40:41]
	v_rndne_f64_e32 v[42:43], v[42:43]
	v_fma_f64 v[40:41], v[4:5], v[40:41], -v[42:43]
	v_cvt_f32_f64_e32 v0, v[40:41]
	v_sin_f32_e32 v40, v0
	v_cos_f32_e32 v0, v0
	v_lshl_add_u64 v[36:37], v[8:9], 0, v[36:37]
	v_mov_b32_e32 v47, v1
	s_waitcnt lgkmcnt(0)
	v_mul_f32_e32 v39, v40, v39
	v_cndmask_b32_e64 v39, v39, -v39, vcc
	v_fmac_f32_e32 v39, v38, v0
	v_lshlrev_b64 v[32:33], 7, v[32:33]
	v_cvt_pk_bf16_f32 v0, v39, s0
	v_lshl_add_u64 v[34:35], v[34:35], 0, v[46:47]
	v_lshl_add_u64 v[32:33], v[36:37], 0, v[32:33]
	s_mov_b64 s[0:1], 0
	global_store_dword v[34:35], v39, off
	global_store_short v[32:33], v0, off
	s_and_saveexec_b64 s[6:7], s[2:3]
	s_xor_b64 s[6:7], exec, s[6:7]
	s_cbranch_execnz .LBB0_230
	s_andn2_saveexec_b64 s[8:9], s[6:7]
	s_cbranch_execnz .LBB0_233

; DEV float sigmf(float x) { return __builtin_amdgcn_rcpf(1.f + __expf(-x)); }
; DEV void phase_m2(const Params& p, int layer) {
;     ...
;     } else if (lane < 16) {
;       AB[(size_t)t * 16 + lane] = sigmf(s[712 + lane - 8]);
.LBB0_230:
	s_and_saveexec_b64 s[8:9], s[4:5]
	s_xor_b64 s[8:9], exec, s[8:9]
	s_cbranch_execz .LBB0_232
	v_mov_b32_e32 v0, v227
	s_mov_b64 s[0:1], exec
	v_mul_f32_e32 v0, 0xbfb8aa3b, v0
	v_exp_f32_e32 v0, v0
	s_nop 0
	v_add_f32_e32 v0, 1.0, v0
	v_rcp_f32_e32 v0, v0

; DEV void phase_m2(const Params& p, int layer) {
;     ...
;     if (lane < 8) {
;       const float a = s[704 + lane] + p.in[9][layer * 8 + lane];
;       const float sp = (a > 20.f) ? a : log1pf(__expf(a));
;       AB[(size_t)t * 16 + lane] = -__expf(p.in[8][layer * 8 + lane]) * sp;
.LBB0_233:
	v_mov_b32_e32 v0, v227
	s_nop 0
	v_mov_b32_e32 v30, v228
	s_mov_b32 s6, 0x41a00000
	v_add_f32_e32 v0, v0, v30
	v_cmp_nlt_f32_e64 s[6:7], s6, v0
	s_and_saveexec_b64 s[10:11], s[6:7]
	s_cbranch_execz .LBB0_235
	v_mul_f32_e32 v0, 0x3fb8aa3b, v0
	v_exp_f32_e32 v0, v0
	s_mov_b32 s6, 0x3f2aaaab
	v_add_f32_e32 v32, 1.0, v0
	v_frexp_mant_f32_e32 v34, v32
	v_cvt_f64_f32_e32 v[30:31], v32
	v_frexp_exp_i32_f64_e32 v30, v[30:31]
	v_cmp_gt_f32_e64 s[6:7], s6, v34
	v_add_f32_e32 v33, -1.0, v32
	v_sub_f32_e32 v35, v33, v32
	v_subbrev_co_u32_e64 v38, s[6:7], 0, v30, s[6:7]
	v_sub_u32_e32 v30, 0, v38
	v_sub_f32_e32 v33, v0, v33
	v_add_f32_e32 v35, 1.0, v35
	v_ldexp_f32 v31, v32, v30
	v_add_f32_e32 v33, v33, v35
	v_add_f32_e32 v32, -1.0, v31
	v_add_f32_e32 v34, 1.0, v31
	v_ldexp_f32 v30, v33, v30
	v_add_f32_e32 v33, 1.0, v32
	v_add_f32_e32 v35, -1.0, v34
	v_sub_f32_e32 v33, v31, v33
	v_sub_f32_e32 v31, v31, v35
	v_add_f32_e32 v33, v30, v33
	v_add_f32_e32 v30, v30, v31
	v_add_f32_e32 v39, v34, v30
	v_rcp_f32_e32 v41, v39
	v_sub_f32_e32 v31, v39, v34
	v_sub_f32_e32 v40, v30, v31
	v_add_f32_e32 v31, v32, v33
	v_mul_f32_e32 v43, v31, v41
	v_sub_f32_e32 v30, v31, v32
	v_mul_f32_e32 v32, v39, v43
	v_fma_f32 v34, v43, v39, -v32
	v_fmac_f32_e32 v34, v43, v40
	v_sub_f32_e32 v42, v33, v30
	v_add_f32_e32 v30, v32, v34
	v_sub_f32_e32 v33, v31, v30
	v_pk_add_f32 v[36:37], v[30:31], v[32:33] neg_lo:[0,1] neg_hi:[0,1]
	v_mov_b32_e32 v35, v30
	v_pk_add_f32 v[30:31], v[36:37], v[34:35] neg_lo:[0,1] neg_hi:[0,1]
	s_mov_b32 s6, 0x3f317218
	v_add_f32_e32 v31, v42, v31
	v_add_f32_e32 v30, v30, v31
	v_add_f32_e32 v31, v33, v30
	v_mul_f32_e32 v42, v41, v31
	v_mul_f32_e32 v32, v39, v42
	v_fma_f32 v34, v42, v39, -v32
	v_fmac_f32_e32 v34, v42, v40
	v_sub_f32_e32 v33, v33, v31
	v_add_f32_e32 v39, v30, v33
	v_add_f32_e32 v30, v32, v34
	v_sub_f32_e32 v33, v31, v30
	v_pk_add_f32 v[36:37], v[30:31], v[32:33] neg_lo:[0,1] neg_hi:[0,1]
	v_mov_b32_e32 v35, v30
	v_pk_add_f32 v[30:31], v[36:37], v[34:35] neg_lo:[0,1] neg_hi:[0,1]
	s_nop 0
	v_add_f32_e32 v31, v39, v31
	v_add_f32_e32 v30, v30, v31
	v_add_f32_e32 v31, v43, v42
	v_add_f32_e32 v30, v33, v30
	v_sub_f32_e32 v32, v31, v43
	v_mul_f32_e32 v30, v41, v30
	v_sub_f32_e32 v32, v42, v32
	v_add_f32_e32 v32, v32, v30
	v_add_f32_e32 v34, v31, v32
	v_mul_f32_e32 v35, v34, v34
	v_mov_b32_e32 v30, 0x3ecc95a3
	v_fmamk_f32 v30, v35, 0x3e9b6dac, v30
	v_fmaak_f32 v161, v35, v30, 0x3f2aaada
	v_cvt_f32_i32_e32 v30, v38
	v_sub_f32_e32 v31, v34, v31
	v_sub_f32_e32 v31, v32, v31
	v_ldexp_f32 v36, v31, 1
	v_mul_f32_e32 v31, v34, v35
	v_ldexp_f32 v33, v34, 1
	v_pk_mul_f32 v[34:35], v[30:31], v[160:161]
	s_nop 0
	v_fma_f32 v32, v30, s6, -v34
	v_fmac_f32_e32 v32, 0xb102e308, v30
	v_pk_add_f32 v[30:31], v[34:35], v[32:33]
	s_mov_b32 s6, 0x7f800000
	v_sub_f32_e32 v33, v31, v33
	v_sub_f32_e32 v33, v35, v33
	v_add_f32_e32 v37, v36, v33
	v_mov_b32_e32 v36, v34
	v_pk_add_f32 v[34:35], v[30:31], v[34:35] neg_lo:[0,1] neg_hi:[0,1]
	v_pk_add_f32 v[38:39], v[30:31], v[36:37]
	v_mov_b32_e32 v33, v30
	v_mov_b32_e32 v35, v39
	v_pk_add_f32 v[40:41], v[32:33], v[34:35] neg_lo:[0,1] neg_hi:[0,1]
	v_pk_add_f32 v[32:33], v[32:33], v[34:35]
	v_mov_b32_e32 v36, v37
	v_pk_add_f32 v[34:35], v[32:33], v[30:31] op_sel:[1,0] op_sel_hi:[0,1] neg_lo:[0,1] neg_hi:[0,1]
	v_pk_add_f32 v[42:43], v[38:39], v[34:35] op_sel_hi:[1,0] neg_lo:[0,1] neg_hi:[0,1]
	v_mov_b32_e32 v38, v39
	v_mov_b32_e32 v39, v33
	v_pk_mov_b32 v[34:35], v[30:31], v[34:35] op_sel:[1,0]
	v_mov_b32_e32 v37, v30
	v_pk_add_f32 v[34:35], v[38:39], v[34:35] neg_lo:[0,1] neg_hi:[0,1]
	v_mov_b32_e32 v42, v40
	v_pk_add_f32 v[30:31], v[36:37], v[34:35] neg_lo:[0,1] neg_hi:[0,1]
	v_mov_b32_e32 v41, v33
	v_pk_add_f32 v[34:35], v[42:43], v[30:31]
	v_cmp_neq_f32_e64 s[6:7], s6, v0
	v_pk_add_f32 v[36:37], v[34:35], v[34:35] op_sel:[0,1] op_sel_hi:[1,0]
	s_nop 0
	v_pk_add_f32 v[32:33], v[32:33], v[36:37] op_sel:[1,0] op_sel_hi:[0,1]
	v_mov_b32_e32 v35, v32
	v_pk_add_f32 v[38:39], v[34:35], v[40:41] neg_lo:[0,1] neg_hi:[0,1]
	v_mov_b32_e32 v31, v36
	v_sub_f32_e32 v33, v34, v38
	v_pk_add_f32 v[30:31], v[30:31], v[38:39] neg_lo:[0,1] neg_hi:[0,1]
	v_sub_f32_e32 v33, v40, v33
	v_add_f32_e32 v30, v30, v33
	v_add_f32_e32 v30, v30, v31
	v_add_f32_e32 v30, v32, v30
	v_cndmask_b32_e64 v30, v210, v30, s[6:7]
	v_cmp_ngt_f32_e64 s[6:7], -1.0, v0
	s_nop 1
	v_cndmask_b32_e64 v30, v211, v30, s[6:7]
	v_cmp_neq_f32_e64 s[6:7], -1.0, v0
	s_nop 1
	v_cndmask_b32_e64 v30, v212, v30, s[6:7]
	s_mov_b32 s6, 0x33800000
	v_cmp_lt_f32_e64 s[6:7], |v0|, s6
	s_nop 1
	v_cndmask_b32_e64 v0, v30, v0, s[6:7]
.LBB0_235:
	s_or_b64 exec, exec, s[10:11]
	v_mov_b32_e32 v30, v229
	s_or_b64 s[0:1], s[0:1], exec
	v_mul_f32_e32 v30, 0x3fb8aa3b, v30
	v_exp_f32_e32 v30, v30
	s_nop 0
	v_mul_f32_e64 v0, v0, -v30
	s_or_b64 exec, exec, s[8:9]
	s_and_saveexec_b64 s[6:7], s[0:1]
	s_cbranch_execz .LBB0_206

; __global__ void __launch_bounds__(256, 2) fwd_megakernel(Params p) {
;   __shared__ __attribute__((aligned(16))) char smem[SMEM_BYTES];
	.amdhsa_kernel _Z14fwd_megakernel6Params
		.amdhsa_group_segment_fixed_size 78912
		.amdhsa_private_segment_fixed_size 0
		.amdhsa_kernarg_size 464
		.amdhsa_user_sgpr_count 2
		.amdhsa_user_sgpr_dispatch_ptr 0
		.amdhsa_user_sgpr_queue_ptr 0
		.amdhsa_user_sgpr_kernarg_segment_ptr 1
		.amdhsa_user_sgpr_dispatch_id 0
		.amdhsa_user_sgpr_kernarg_preload_length 0
		.amdhsa_user_sgpr_kernarg_preload_offset 0
		.amdhsa_user_sgpr_private_segment_size 0
		.amdhsa_uses_dynamic_stack 0
		.amdhsa_enable_private_segment 0
		.amdhsa_system_sgpr_workgroup_id_x 1
		.amdhsa_system_sgpr_workgroup_id_y 0
		.amdhsa_system_sgpr_workgroup_id_z 0
		.amdhsa_system_sgpr_workgroup_info 0
		.amdhsa_system_vgpr_workitem_id 2
		.amdhsa_next_free_vgpr 256
		.amdhsa_next_free_sgpr 102
		.amdhsa_accum_offset 256
		.amdhsa_reserve_vcc 1
		.amdhsa_float_round_mode_32 0
		.amdhsa_float_round_mode_16_64 0
		.amdhsa_float_denorm_mode_32 3
		.amdhsa_float_denorm_mode_16_64 3
		.amdhsa_dx10_clamp 1
		.amdhsa_ieee_mode 1
		.amdhsa_fp16_overflow 0
		.amdhsa_tg_split 0
		.amdhsa_exception_fp_ieee_invalid_op 0
		.amdhsa_exception_fp_denorm_src 0
		.amdhsa_exception_fp_ieee_div_zero 0
		.amdhsa_exception_fp_ieee_overflow 0
		.amdhsa_exception_fp_ieee_underflow 0
		.amdhsa_exception_fp_ieee_inexact 0
		.amdhsa_exception_int_div_zero 0
	.end_amdhsa_kernel

; __global__ void __launch_bounds__(256, 2) fwd_megakernel(Params p) {
;   __shared__ __attribute__((aligned(16))) char smem[SMEM_BYTES];
amdhsa.kernels:
  - .agpr_count:     0
    .args:
      - .offset:         0
        .size:           208
        .value_kind:     by_value
      - .offset:         208
        .size:           4
        .value_kind:     hidden_block_count_x
      - .offset:         212
        .size:           4
        .value_kind:     hidden_block_count_y
      - .offset:         216
        .size:           4
        .value_kind:     hidden_block_count_z
      - .offset:         220
        .size:           2
        .value_kind:     hidden_group_size_x
      - .offset:         222
        .size:           2
        .value_kind:     hidden_group_size_y
      - .offset:         224
        .size:           2
        .value_kind:     hidden_group_size_z
      - .offset:         226
        .size:           2
        .value_kind:     hidden_remainder_x
      - .offset:         228
        .size:           2
        .value_kind:     hidden_remainder_y
      - .offset:         230
        .size:           2
        .value_kind:     hidden_remainder_z
      - .offset:         248
        .size:           8
        .value_kind:     hidden_global_offset_x
      - .offset:         256
        .size:           8
        .value_kind:     hidden_global_offset_y
      - .offset:         264
        .size:           8
        .value_kind:     hidden_global_offset_z
      - .offset:         272
        .size:           2
        .value_kind:     hidden_grid_dims
      - .offset:         296
        .size:           8
        .value_kind:     hidden_multigrid_sync_arg
    .group_segment_fixed_size: 78912
    .kernarg_segment_align: 8
    .kernarg_segment_size: 464
    .language:       OpenCL C
    .language_version:
      - 2
      - 0
    .max_flat_workgroup_size: 256
    .name:           _Z14fwd_megakernel6Params
    .private_segment_fixed_size: 0
    .sgpr_count:     108
    .sgpr_spill_count: 120
    .symbol:         _Z14fwd_megakernel6Params.kd
    .uniform_work_group_size: 1
    .uses_dynamic_stack: false
    .vgpr_count:     256
    .vgpr_spill_count: 0
    .wavefront_size: 64
